# PD: latent SSM pass-2 jobs remapped onto the workgroups with the lightest GEMM share (c0 in [32,160)); chunk-carry states prefetched (7 loads at once) instead of one serial load per chunk
# speedup vs baseline: 1.0151x; 1.0040x over previous
.LBB0_500:
	v_readlane_b32 s0, v251, 11
	s_add_i32 s67, s27, s0
	s_cmpk_lg_u32 s26, 0x100
	s_cbranch_scc1 .Lssb_map_done
	s_addk_i32 s67, 0xff00
	s_cmp_lt_i32 s67, 0
	s_cbranch_scc0 .Lssb_map_done
	s_addk_i32 s67, 0x600
.Lssb_map_done:
	s_cmpk_gt_i32 s67, 0x3ff
	s_cbranch_scc1 .LBB0_519
	v_readlane_b32 s6, v251, 13
	v_lshlrev_b32_e32 v0, 4, v204
	v_readlane_b32 s7, v251, 14
	v_lshrrev_b32_e32 v6, 5, v204
	v_and_b32_e32 v124, 31, v240
	v_lshl_add_u64 v[100:101], s[6:7], 0, v[0:1]
	v_readlane_b32 s6, v251, 15
	v_lshlrev_b32_e32 v0, 4, v6
	v_readlane_b32 s7, v251, 16
	v_lshlrev_b32_e32 v4, 5, v124
	v_mov_b32_e32 v5, v1
	v_lshl_add_u64 v[2:3], s[6:7], 0, v[0:1]
	v_lshl_add_u64 v[102:103], v[2:3], 0, v[4:5]
	v_lshlrev_b32_e32 v2, 8, v204
	v_readlane_b32 s6, v251, 17
	v_and_b32_e32 v2, 0xf00, v2
	v_mov_b32_e32 v3, v1
	v_readlane_b32 s7, v251, 18
	s_mul_i32 s0, s27, 0x3200
	s_mov_b32 s3, s31
	v_lshl_add_u64 v[2:3], s[6:7], 0, v[2:3]
	v_readlane_b32 s6, v249, 15
	v_readlane_b32 s7, v249, 16
	v_and_b32_e32 v126, 15, v240
	s_add_i32 s2, s0, 0
	s_bfe_u32 s20, s3, 0x30006
	v_and_b32_e32 v4, 48, v240
	v_lshl_add_u64 v[106:107], s[6:7], 0, v[0:1]
	v_mul_u32_u24_e32 v0, 0x110, v126
	s_ashr_i32 s31, s30, 31
	s_lshl_b32 s22, s20, 8
	v_lshl_add_u64 v[104:105], v[2:3], 0, v[4:5]
	v_lshl_add_u32 v3, v124, 2, s2
	v_lshl_add_u32 v125, v204, 2, s2
	v_add3_u32 v127, s2, v0, v4
	v_readlane_b32 s2, v251, 19
	s_lshl_b32 s72, s30, 6
	s_lshl_b64 s[0:1], s[30:31], 1
	s_xor_b32 s23, s22, 0x700
	v_lshrrev_b32_e32 v0, 2, v240
	v_lshlrev_b32_e32 v108, 3, v204
	v_mov_b32_e32 v109, v1
	v_readlane_b32 s3, v251, 20
	s_cmp_lg_u32 s20, 0
	v_lshlrev_b32_e32 v5, 11, v6
	v_and_b32_e32 v0, 12, v0
	v_lshlrev_b32_e32 v2, 1, v204
	v_lshl_add_u64 v[110:111], s[2:3], 0, v[108:109]
	s_movk_i32 s2, 0xff
	s_cselect_b64 s[50:51], -1, 0
	v_sub_u32_e32 v109, 0, v126
	v_bitop3_b32 v128, v240, s2, 31 bitop3:0x6c
	v_lshlrev_b32_e32 v129, 2, v2
	v_lshlrev_b32_e32 v0, 1, v0
	v_add_u32_e32 v130, v3, v5
	s_branch .LBB0_503

.LBB0_509:
	s_andn2_b64 vcc, exec, s[8:9]
	s_cbranch_vccnz .LBB0_514
	s_mov_b32 s7, s4
	s_lshl_b64 s[8:9], s[6:7], 3
	s_add_u32 s5, s8, s0
	s_addc_u32 s9, s9, s1
	s_or_b32 s8, s5, s73
	v_readlane_b32 s80, v254, 48
	s_lshl_b64 s[8:9], s[8:9], 14
	v_readlane_b32 s88, v254, 56
	v_readlane_b32 s89, v254, 57
	s_add_u32 s5, s88, s8
	s_addc_u32 s9, s89, s9
	s_lshl_b32 s8, s53, 9
	s_add_u32 s8, s5, s8
	s_addc_u32 s9, s9, 0
	global_load_dwordx2 v[122:123], v129, s[8:9]
	s_andn2_b64 vcc, exec, s[50:51]
	v_readlane_b32 s81, v254, 49
	v_readlane_b32 s82, v254, 50
	v_readlane_b32 s83, v254, 51
	v_readlane_b32 s84, v254, 52
	v_readlane_b32 s85, v254, 53
	v_readlane_b32 s86, v254, 54
	v_readlane_b32 s87, v254, 55
	v_readlane_b32 s90, v254, 58
	v_readlane_b32 s91, v254, 59
	v_readlane_b32 s92, v254, 60
	v_readlane_b32 s93, v254, 61
	v_readlane_b32 s94, v254, 62
	v_readlane_b32 s95, v254, 63
	s_cbranch_vccnz .LBB0_513
	s_lshr_b32 s5, s67, 8
	s_and_b32 s5, s5, 1
	s_lshr_b32 s8, s67, 3
	s_lshl_b64 s[6:7], s[6:7], 6
	s_lshl_b32 s5, s5, 5
	s_and_b32 s8, s8, 31
	s_or_b32 s5, s6, s5
	s_or_b32 s6, s5, s8
	s_lshl_b64 s[6:7], s[6:7], 12
	v_lshl_add_u64 v[4:5], v[110:111], 0, s[6:7]
	global_load_dwordx2 v[160:161], v[4:5], off
	global_load_dwordx2 v[162:163], v[4:5], off offset:512
	global_load_dwordx2 v[164:165], v[4:5], off offset:1024
	global_load_dwordx2 v[166:167], v[4:5], off offset:1536
	global_load_dwordx2 v[168:169], v[4:5], off offset:2048
	global_load_dwordx2 v[170:171], v[4:5], off offset:2560
	global_load_dwordx2 v[172:173], v[4:5], off offset:3072
	s_waitcnt vmcnt(0)
	v_pk_mov_b32 v[2:3], v[68:69], v[68:69] op_sel:[1,0]
	s_nop 0
	v_mov_b32_e32 v6, v123
	v_pk_mul_f32 v[6:7], v[2:3], v[6:7] op_sel_hi:[1,0]
	s_nop 0
	v_pk_fma_f32 v[8:9], v[68:69], v[122:123], v[6:7] neg_lo:[0,0,1] neg_hi:[0,0,1]
	v_pk_fma_f32 v[6:7], v[68:69], v[122:123], v[6:7] op_sel_hi:[1,0,1]
	s_nop 0
	v_mov_b32_e32 v9, v7
	s_nop 0
	v_pk_add_f32 v[122:123], v[8:9], v[160:161]
	s_nop 0
	v_mov_b32_e32 v6, v123
	s_cmp_eq_u32 s20, 1
	s_cbranch_scc1 .Lssb_carry_done
	v_pk_mul_f32 v[6:7], v[2:3], v[6:7] op_sel_hi:[1,0]
	s_nop 0
	v_pk_fma_f32 v[8:9], v[68:69], v[122:123], v[6:7] neg_lo:[0,0,1] neg_hi:[0,0,1]
	v_pk_fma_f32 v[6:7], v[68:69], v[122:123], v[6:7] op_sel_hi:[1,0,1]
	s_nop 0
	v_mov_b32_e32 v9, v7
	s_nop 0
	v_pk_add_f32 v[122:123], v[8:9], v[162:163]
	s_nop 0
	v_mov_b32_e32 v6, v123
	s_cmp_eq_u32 s20, 2
	s_cbranch_scc1 .Lssb_carry_done
	v_pk_mul_f32 v[6:7], v[2:3], v[6:7] op_sel_hi:[1,0]
	s_nop 0
	v_pk_fma_f32 v[8:9], v[68:69], v[122:123], v[6:7] neg_lo:[0,0,1] neg_hi:[0,0,1]
	v_pk_fma_f32 v[6:7], v[68:69], v[122:123], v[6:7] op_sel_hi:[1,0,1]
	s_nop 0
	v_mov_b32_e32 v9, v7
	s_nop 0
	v_pk_add_f32 v[122:123], v[8:9], v[164:165]
	s_nop 0
	v_mov_b32_e32 v6, v123
	s_cmp_eq_u32 s20, 3
	s_cbranch_scc1 .Lssb_carry_done
	v_pk_mul_f32 v[6:7], v[2:3], v[6:7] op_sel_hi:[1,0]
	s_nop 0
	v_pk_fma_f32 v[8:9], v[68:69], v[122:123], v[6:7] neg_lo:[0,0,1] neg_hi:[0,0,1]
	v_pk_fma_f32 v[6:7], v[68:69], v[122:123], v[6:7] op_sel_hi:[1,0,1]
	s_nop 0
	v_mov_b32_e32 v9, v7
	s_nop 0
	v_pk_add_f32 v[122:123], v[8:9], v[166:167]
	s_nop 0
	v_mov_b32_e32 v6, v123
	s_cmp_eq_u32 s20, 4
	s_cbranch_scc1 .Lssb_carry_done
	v_pk_mul_f32 v[6:7], v[2:3], v[6:7] op_sel_hi:[1,0]
	s_nop 0
	v_pk_fma_f32 v[8:9], v[68:69], v[122:123], v[6:7] neg_lo:[0,0,1] neg_hi:[0,0,1]
	v_pk_fma_f32 v[6:7], v[68:69], v[122:123], v[6:7] op_sel_hi:[1,0,1]
	s_nop 0
	v_mov_b32_e32 v9, v7
	s_nop 0
	v_pk_add_f32 v[122:123], v[8:9], v[168:169]
	s_nop 0
	v_mov_b32_e32 v6, v123
	s_cmp_eq_u32 s20, 5
	s_cbranch_scc1 .Lssb_carry_done
	v_pk_mul_f32 v[6:7], v[2:3], v[6:7] op_sel_hi:[1,0]
	s_nop 0
	v_pk_fma_f32 v[8:9], v[68:69], v[122:123], v[6:7] neg_lo:[0,0,1] neg_hi:[0,0,1]
	v_pk_fma_f32 v[6:7], v[68:69], v[122:123], v[6:7] op_sel_hi:[1,0,1]
	s_nop 0
	v_mov_b32_e32 v9, v7
	s_nop 0
	v_pk_add_f32 v[122:123], v[8:9], v[170:171]
	s_nop 0
	v_mov_b32_e32 v6, v123
	s_cmp_eq_u32 s20, 6
	s_cbranch_scc1 .Lssb_carry_done
	v_pk_mul_f32 v[6:7], v[2:3], v[6:7] op_sel_hi:[1,0]
	s_nop 0
	v_pk_fma_f32 v[8:9], v[68:69], v[122:123], v[6:7] neg_lo:[0,0,1] neg_hi:[0,0,1]
	v_pk_fma_f32 v[6:7], v[68:69], v[122:123], v[6:7] op_sel_hi:[1,0,1]
	s_nop 0
	v_mov_b32_e32 v9, v7
	s_nop 0
	v_pk_add_f32 v[122:123], v[8:9], v[172:173]
	s_nop 0
	v_mov_b32_e32 v6, v123
.Lssb_carry_done:
.LBB0_513:
	s_mov_b32 s52, s4
	s_branch .LBB0_515
